# ret_scan row sums: the 16 per-step zero-inits in front of full-permutation DPP moves (quad_perm / row_mirror, all rows and banks, exec full) removed as dead
# speedup vs baseline: 1.0031x; 1.0031x over previous
; #define RET_LOAD(X, nn) do { const bf16_t* r_ = gsrc + (size_t)(nn) * 64 * 1536; X[0] = *(const u32x4*)(r_ + h * 64 + ld0); X[1] = *(const u32x4*)(r_ + 256 + h * 64 + ld0); \
;         X[2] = *(const u32x4*)(r_ + 512 + h * 128 + lc0); X[3] = *(const u32x4*)(r_ + 512 + h * 128 + lc0 + 8); } while (0)
; #define RET_STORE(X, bufi) do { bf16_t* B_ = (bf16_t*)(lds + (bufi) * RB); *(u32x4*)(B_ + li * 72 + ld0) = X[0]; *(u32x4*)(B_ + 64 * 72 + li * 72 + ld0) = X[1]; \
;         *(u32x4*)(B_ + 128 * 72 + li * 136 + lc0) = X[2]; *(u32x4*)(B_ + 128 * 72 + li * 136 + lc0 + 8) = X[3]; } while (0)
; DI void ret_scan_wg(const Params& p, int l, int bhi, unsigned char* lds, int tid) {
;     ...
;     u32x4 stA[4], stB[4];
;     RET_LOAD(stA, 0); RET_LOAD(stB, 1); RET_STORE(stA, 0); RET_STORE(stB, 1); RET_LOAD(stA, 2);
;     __syncthreads();
;     RET_PTILE(0);
;     __syncthreads();
.LBB0_199:
	s_or_b64 exec, exec, s[48:49]
	s_mul_i32 s4, s22, 0xab
	s_bfe_u32 s4, s4, 0x70009
	s_mul_i32 s4, s4, 3
	s_sub_i32 s4, s22, s4
	v_cvt_pk_bf16_f32 v58, v58, v59
	v_cvt_pk_bf16_f32 v59, v60, v61
	s_and_b32 s4, s4, 0xff
	ds_write_b64 v116, v[58:59]
	v_ashrrev_i32_e32 v58, 2, v97
	v_lshlrev_b32_e32 v83, 2, v96
	s_mul_i32 s4, s4, 0x8c00
	v_add_u32_e32 v119, v58, v83
	v_lshlrev_b32_e32 v58, 3, v97
	v_add_u32_e32 v62, s4, v168
	v_and_b32_e32 v58, 24, v58
	v_mul_lo_u32 v59, v119, s65
	v_add_u32_e32 v132, v62, v58
	v_add3_u32 v58, v132, v118, v59
	v_lshl_add_u32 v134, v96, 3, v62
	v_add_u32_e32 v62, v144, v108
	ds_read_b64_tr_b16 v[136:137], v58 offset:18432
	ds_read_b64_tr_b16 v[138:139], v58 offset:22784
	ds_read_b64_tr_b16 v[152:153], v58 offset:27136
	ds_read_b64_tr_b16 v[154:155], v58 offset:31488
	ds_read_b128 v[156:159], v62
	v_add_u32_e32 v140, s45, v97
	v_mad_u64_u32 v[160:161], s[4:5], v140, s56, v[134:135]
	ds_read2_b64 v[170:173], v160 offset1:4
	ds_read2_b64 v[174:177], v160 offset0:8 offset1:12
	v_add_u32_e32 v141, v144, v114
	ds_read_b128 v[178:181], v141 offset:1024
	ds_read_b128 v[182:185], v141
	v_add_u32_e32 v142, s43, v97
	v_mad_u64_u32 v[162:163], s[4:5], v142, s56, v[134:135]
	ds_read2_b64 v[186:189], v162 offset1:4
	ds_read2_b64 v[190:193], v162 offset0:8 offset1:12
	v_mad_u64_u32 v[194:195], s[4:5], v119, s56, v[132:133]
	ds_read_b64_tr_b16 v[196:197], v194 offset:9216
	ds_read_b64_tr_b16 v[200:201], v194 offset:9248
	ds_read_b64_tr_b16 v[198:199], v194 offset:11520
	ds_read_b64_tr_b16 v[212:213], v194 offset:13824
	ds_read_b64_tr_b16 v[214:215], v194 offset:16128
	ds_read_b64_tr_b16 v[202:203], v194 offset:11552
	ds_read_b64_tr_b16 v[216:217], v194 offset:13856
	ds_read_b64_tr_b16 v[218:219], v194 offset:16160
	ds_read_b64_tr_b16 v[220:221], v194 offset:9280
	ds_read_b64_tr_b16 v[222:223], v194 offset:11584
	ds_read_b64_tr_b16 v[224:225], v194 offset:13888
	ds_read_b64_tr_b16 v[226:227], v194 offset:16192
	ds_read_b64_tr_b16 v[228:229], v194 offset:9312
	ds_read_b64_tr_b16 v[230:231], v194 offset:11616
	ds_read_b64_tr_b16 v[232:233], v194 offset:13920
	ds_read_b64_tr_b16 v[234:235], v194 offset:16224
	s_waitcnt lgkmcnt(15)
	v_mfma_f32_16x16x32_bf16 v[62:65], v[156:159], v[136:139], v[0:3]
	v_cvt_pk_bf16_f32 v58, v50, v51
	v_cvt_pk_bf16_f32 v59, v52, v53
	v_cvt_pk_bf16_f32 v60, v38, v39
	v_cvt_pk_bf16_f32 v61, v40, v41
	v_cvt_pk_bf16_f32 v120, v42, v43
	v_cvt_pk_bf16_f32 v121, v44, v45
	s_waitcnt lgkmcnt(15)
	v_mfma_f32_16x16x32_bf16 v[62:65], v[170:173], v[58:61], v[62:65]
	v_cvt_pk_bf16_f32 v122, v54, v55
	v_cvt_pk_bf16_f32 v123, v56, v57
	s_waitcnt lgkmcnt(15)
	s_nop 1
	v_mfma_f32_16x16x32_bf16 v[62:65], v[174:177], v[120:123], v[62:65]
	s_waitcnt lgkmcnt(15)
	v_mfma_f32_16x16x32_bf16 v[124:127], v[182:185], v[136:139], v[0:3]
	v_mov_b32_e32 v81, v80
	v_pk_mul_f32 v[52:53], v[80:81], v[52:53]
	v_pk_mul_f32 v[50:51], v[84:85], v[50:51]
	s_waitcnt lgkmcnt(15)
	v_mfma_f32_16x16x32_bf16 v[124:127], v[178:181], v[152:155], v[124:127]
	v_pk_mul_f32 v[40:41], v[80:81], v[40:41]
	v_pk_mul_f32 v[38:39], v[84:85], v[38:39]
	s_waitcnt lgkmcnt(15)
	v_mfma_f32_16x16x32_bf16 v[58:61], v[186:189], v[58:61], v[124:127]
	s_nop 2
	s_waitcnt lgkmcnt(15)
	v_mfma_f32_16x16x32_bf16 v[58:61], v[190:193], v[120:123], v[58:61]
	v_pk_mul_f32 v[44:45], v[80:81], v[44:45]
	v_pk_mul_f32 v[42:43], v[84:85], v[42:43]
	s_waitcnt lgkmcnt(13)
	v_mfma_f32_16x16x32_bf16 v[50:53], v[196:199], v[136:139], v[50:53]
	v_pk_mul_f32 v[56:57], v[80:81], v[56:57]
	s_waitcnt lgkmcnt(11)
	v_mfma_f32_16x16x32_bf16 v[50:53], v[212:215], v[152:155], v[50:53]
	v_pk_mul_f32 v[54:55], v[84:85], v[54:55]
	v_cmp_eq_u32_e32 vcc, 0, v97
	s_waitcnt lgkmcnt(10)
	v_mfma_f32_16x16x32_bf16 v[38:41], v[200:203], v[136:139], v[38:41]
	s_waitcnt lgkmcnt(8)
	v_mfma_f32_16x16x32_bf16 v[38:41], v[216:219], v[152:155], v[38:41]
	s_waitcnt lgkmcnt(6)
	v_mfma_f32_16x16x32_bf16 v[42:45], v[220:223], v[136:139], v[42:45]
	s_waitcnt lgkmcnt(4)
	v_mfma_f32_16x16x32_bf16 v[42:45], v[224:227], v[152:155], v[42:45]
	s_waitcnt lgkmcnt(2)
	v_mfma_f32_16x16x32_bf16 v[54:57], v[228:231], v[136:139], v[54:57]
	s_waitcnt lgkmcnt(0)
	v_mfma_f32_16x16x32_bf16 v[54:57], v[232:235], v[152:155], v[54:57]
	v_mul_f32_e32 v170, v62, v62
	v_mul_f32_e32 v171, v63, v63
	v_mul_f32_e32 v172, v64, v64
	v_mul_f32_e32 v173, v65, v65
	v_mul_f32_e32 v174, v58, v58
	v_mul_f32_e32 v175, v59, v59
	v_mul_f32_e32 v176, v60, v60
	v_mul_f32_e32 v177, v61, v61
	v_add_u32_e32 v66, v83, v112
	v_lshl_add_u32 v66, v66, 2, v143
	v_mov_b32_dpp v178, v170 quad_perm:[1,0,3,2] row_mask:0xf bank_mask:0xf
	v_mov_b32_dpp v179, v171 quad_perm:[1,0,3,2] row_mask:0xf bank_mask:0xf
	v_mov_b32_dpp v180, v172 quad_perm:[1,0,3,2] row_mask:0xf bank_mask:0xf
	v_mov_b32_dpp v181, v173 quad_perm:[1,0,3,2] row_mask:0xf bank_mask:0xf
	v_mov_b32_dpp v182, v174 quad_perm:[1,0,3,2] row_mask:0xf bank_mask:0xf
	v_mov_b32_dpp v183, v175 quad_perm:[1,0,3,2] row_mask:0xf bank_mask:0xf
	v_mov_b32_dpp v184, v176 quad_perm:[1,0,3,2] row_mask:0xf bank_mask:0xf
	v_mov_b32_dpp v185, v177 quad_perm:[1,0,3,2] row_mask:0xf bank_mask:0xf
	v_fmac_f32_e32 v178, v62, v62
	v_fmac_f32_e32 v179, v63, v63
	v_fmac_f32_e32 v180, v64, v64
	v_fmac_f32_e32 v181, v65, v65
	v_fmac_f32_e32 v182, v58, v58
	v_fmac_f32_e32 v183, v59, v59
	v_fmac_f32_e32 v184, v60, v60
	v_fmac_f32_e32 v185, v61, v61
	v_add_f32_dpp v170, v178, v178 quad_perm:[2,3,0,1] row_mask:0xf bank_mask:0xf bound_ctrl:1
	v_add_f32_dpp v171, v179, v179 quad_perm:[2,3,0,1] row_mask:0xf bank_mask:0xf bound_ctrl:1
	v_add_f32_dpp v172, v180, v180 quad_perm:[2,3,0,1] row_mask:0xf bank_mask:0xf bound_ctrl:1
	v_add_f32_dpp v173, v181, v181 quad_perm:[2,3,0,1] row_mask:0xf bank_mask:0xf bound_ctrl:1
	v_add_f32_dpp v174, v182, v182 quad_perm:[2,3,0,1] row_mask:0xf bank_mask:0xf bound_ctrl:1
	v_add_f32_dpp v175, v183, v183 quad_perm:[2,3,0,1] row_mask:0xf bank_mask:0xf bound_ctrl:1
	v_add_f32_dpp v176, v184, v184 quad_perm:[2,3,0,1] row_mask:0xf bank_mask:0xf bound_ctrl:1
	v_add_f32_dpp v177, v185, v185 quad_perm:[2,3,0,1] row_mask:0xf bank_mask:0xf bound_ctrl:1
	v_add_f32_dpp v170, v170, v170 row_half_mirror row_mask:0xf bank_mask:0xf bound_ctrl:1
	v_add_f32_dpp v171, v171, v171 row_half_mirror row_mask:0xf bank_mask:0xf bound_ctrl:1
	v_add_f32_dpp v172, v172, v172 row_half_mirror row_mask:0xf bank_mask:0xf bound_ctrl:1
	v_add_f32_dpp v173, v173, v173 row_half_mirror row_mask:0xf bank_mask:0xf bound_ctrl:1
	v_add_f32_dpp v174, v174, v174 row_half_mirror row_mask:0xf bank_mask:0xf bound_ctrl:1
	v_add_f32_dpp v175, v175, v175 row_half_mirror row_mask:0xf bank_mask:0xf bound_ctrl:1
	v_add_f32_dpp v176, v176, v176 row_half_mirror row_mask:0xf bank_mask:0xf bound_ctrl:1
	v_add_f32_dpp v177, v177, v177 row_half_mirror row_mask:0xf bank_mask:0xf bound_ctrl:1
	v_mov_b32_dpp v178, v170 row_mirror row_mask:0xf bank_mask:0xf
	v_mov_b32_dpp v179, v171 row_mirror row_mask:0xf bank_mask:0xf
	v_mov_b32_dpp v180, v172 row_mirror row_mask:0xf bank_mask:0xf
	v_mov_b32_dpp v181, v173 row_mirror row_mask:0xf bank_mask:0xf
	v_mov_b32_dpp v182, v174 row_mirror row_mask:0xf bank_mask:0xf
	v_mov_b32_dpp v183, v175 row_mirror row_mask:0xf bank_mask:0xf
	v_mov_b32_dpp v184, v176 row_mirror row_mask:0xf bank_mask:0xf
	v_mov_b32_dpp v185, v177 row_mirror row_mask:0xf bank_mask:0xf
	s_and_saveexec_b64 s[4:5], vcc
	v_add_f32_e32 v170, v170, v178
	v_add_f32_e32 v171, v171, v179
	v_add_f32_e32 v172, v172, v180
	v_add_f32_e32 v173, v173, v181
	v_add_f32_e32 v174, v174, v182
	v_add_f32_e32 v175, v175, v183
	v_add_f32_e32 v176, v176, v184
	v_add_f32_e32 v177, v177, v185
	ds_write_b32 v66, v170
	ds_write_b32 v66, v171 offset:4
	ds_write_b32 v66, v172 offset:8
	ds_write_b32 v66, v173 offset:12
	ds_write_b32 v66, v174 offset:64
	ds_write_b32 v66, v175 offset:68
	ds_write_b32 v66, v176 offset:72
	ds_write_b32 v66, v177 offset:76
	s_or_b64 exec, exec, s[4:5]
	s_add_i32 s23, s22, 2
	s_cmp_lt_u32 s22, 30
	s_cselect_b64 s[50:51], -1, 0
	s_cmp_gt_u32 s22, 29
	s_cselect_b64 s[48:49], -1, 0
	s_and_b64 vcc, exec, s[48:49]
	v_lshlrev_b32_e32 v119, 1, v164
	s_cbranch_vccnz .LBB0_217
	s_mul_i32 s4, s23, 0xab
	s_bfe_u32 s4, s4, 0x70009
	s_mul_i32 s4, s4, 3
	s_sub_i32 s4, s23, s4
	s_and_b32 s4, s4, 0xff
	s_mul_i32 s4, s4, 0x8c00
	v_add_u32_e32 v66, s4, v76
	v_lshl_add_u32 v67, v106, 1, v66
	v_add3_u32 v66, v66, v77, v119
	s_cmp_eq_u32 s22, 0
	s_cbranch_scc0 .Lrv_b1_n0
	s_waitcnt vmcnt(4)
	s_branch .Lrv_b1_end

.LBB0_227:
	s_bfe_u32 s4, s37, 0x70009
	s_mul_i32 s4, s4, 3
	s_sub_i32 s4, s36, s4
	s_and_b32 s4, s4, 0xff
	v_ashrrev_i32_e32 v58, 2, v121
	v_lshlrev_b32_e32 v83, 2, v120
	s_mul_i32 s4, s4, 0x8c00
	v_add_u32_e32 v95, v58, v83
	v_lshlrev_b32_e32 v58, 3, v121
	v_add_u32_e32 v62, s4, v168
	v_and_b32_e32 v58, 24, v58
	v_mul_lo_u32 v59, v95, s65
	v_add_u32_e32 v94, v62, v58
	v_add3_u32 v58, v94, v118, v59
	v_lshl_add_u32 v130, v120, 3, v62
	v_add_u32_e32 v62, v145, v108
	ds_read_b64_tr_b16 v[136:137], v58 offset:18432
	ds_read_b64_tr_b16 v[138:139], v58 offset:22784
	ds_read_b64_tr_b16 v[152:153], v58 offset:27136
	ds_read_b64_tr_b16 v[154:155], v58 offset:31488
	ds_read_b128 v[156:159], v62
	v_add_u32_e32 v140, s45, v121
	v_mad_u64_u32 v[160:161], s[4:5], v140, s56, v[130:131]
	ds_read2_b64 v[170:173], v160 offset1:4
	ds_read2_b64 v[174:177], v160 offset0:8 offset1:12
	v_add_u32_e32 v141, v145, v114
	ds_read_b128 v[178:181], v141 offset:1024
	ds_read_b128 v[182:185], v141
	v_add_u32_e32 v142, s43, v121
	v_mad_u64_u32 v[162:163], s[4:5], v142, s56, v[130:131]
	v_mad_u64_u32 v[186:187], s[4:5], v95, s56, v[94:95]
	ds_read2_b64 v[188:191], v162 offset1:4
	ds_read2_b64 v[192:195], v162 offset0:8 offset1:12
	ds_read_b64_tr_b16 v[196:197], v186 offset:9216
	ds_read_b64_tr_b16 v[200:201], v186 offset:9248
	ds_read_b64_tr_b16 v[198:199], v186 offset:11520
	ds_read_b64_tr_b16 v[212:213], v186 offset:13824
	ds_read_b64_tr_b16 v[214:215], v186 offset:16128
	ds_read_b64_tr_b16 v[202:203], v186 offset:11552
	ds_read_b64_tr_b16 v[216:217], v186 offset:13856
	ds_read_b64_tr_b16 v[218:219], v186 offset:16160
	ds_read_b64_tr_b16 v[220:221], v186 offset:9280
	ds_read_b64_tr_b16 v[222:223], v186 offset:11584
	ds_read_b64_tr_b16 v[224:225], v186 offset:13888
	ds_read_b64_tr_b16 v[226:227], v186 offset:16192
	ds_read_b64_tr_b16 v[228:229], v186 offset:9312
	ds_read_b64_tr_b16 v[230:231], v186 offset:11616
	ds_read_b64_tr_b16 v[232:233], v186 offset:13920
	ds_read_b64_tr_b16 v[234:235], v186 offset:16224
	s_waitcnt lgkmcnt(15)
	v_mfma_f32_16x16x32_bf16 v[62:65], v[156:159], v[136:139], v[0:3]
	v_cvt_pk_bf16_f32 v58, v50, v51
	v_cvt_pk_bf16_f32 v59, v52, v53
	v_cvt_pk_bf16_f32 v60, v38, v39
	v_cvt_pk_bf16_f32 v61, v40, v41
	v_cvt_pk_bf16_f32 v98, v42, v43
	v_cvt_pk_bf16_f32 v99, v44, v45
	s_waitcnt lgkmcnt(15)
	v_mfma_f32_16x16x32_bf16 v[62:65], v[170:173], v[58:61], v[62:65]
	v_cvt_pk_bf16_f32 v100, v54, v55
	v_cvt_pk_bf16_f32 v101, v56, v57
	s_waitcnt lgkmcnt(15)
	s_nop 1
	v_mfma_f32_16x16x32_bf16 v[62:65], v[174:177], v[98:101], v[62:65]
	s_waitcnt lgkmcnt(15)
	v_mfma_f32_16x16x32_bf16 v[122:125], v[182:185], v[136:139], v[0:3]
	v_mov_b32_e32 v81, v80
	s_waitcnt lgkmcnt(15)
	v_mfma_f32_16x16x32_bf16 v[122:125], v[178:181], v[152:155], v[122:125]
	v_pk_mul_f32 v[52:53], v[80:81], v[52:53]
	v_pk_mul_f32 v[50:51], v[84:85], v[50:51]
	s_waitcnt lgkmcnt(15)
	v_mfma_f32_16x16x32_bf16 v[58:61], v[188:191], v[58:61], v[122:125]
	s_nop 2
	v_pk_mul_f32 v[40:41], v[80:81], v[40:41]
	v_pk_mul_f32 v[38:39], v[84:85], v[38:39]
	s_waitcnt lgkmcnt(15)
	v_mfma_f32_16x16x32_bf16 v[58:61], v[192:195], v[98:101], v[58:61]
	v_pk_mul_f32 v[44:45], v[80:81], v[44:45]
	v_pk_mul_f32 v[42:43], v[84:85], v[42:43]
	s_waitcnt lgkmcnt(13)
	v_mfma_f32_16x16x32_bf16 v[50:53], v[196:199], v[136:139], v[50:53]
	v_pk_mul_f32 v[56:57], v[80:81], v[56:57]
	s_waitcnt lgkmcnt(11)
	v_mfma_f32_16x16x32_bf16 v[50:53], v[212:215], v[152:155], v[50:53]
	v_pk_mul_f32 v[54:55], v[84:85], v[54:55]
	v_cmp_eq_u32_e32 vcc, 0, v121
	s_waitcnt lgkmcnt(10)
	v_mfma_f32_16x16x32_bf16 v[38:41], v[200:203], v[136:139], v[38:41]
	s_waitcnt lgkmcnt(8)
	v_mfma_f32_16x16x32_bf16 v[38:41], v[216:219], v[152:155], v[38:41]
	s_waitcnt lgkmcnt(6)
	v_mfma_f32_16x16x32_bf16 v[42:45], v[220:223], v[136:139], v[42:45]
	s_waitcnt lgkmcnt(4)
	v_mfma_f32_16x16x32_bf16 v[42:45], v[224:227], v[152:155], v[42:45]
	s_waitcnt lgkmcnt(2)
	v_mfma_f32_16x16x32_bf16 v[54:57], v[228:231], v[136:139], v[54:57]
	s_waitcnt lgkmcnt(0)
	v_mfma_f32_16x16x32_bf16 v[54:57], v[232:235], v[152:155], v[54:57]
	v_mul_f32_e32 v170, v62, v62
	v_mul_f32_e32 v171, v63, v63
	v_mul_f32_e32 v172, v64, v64
	v_mul_f32_e32 v173, v65, v65
	v_mul_f32_e32 v174, v58, v58
	v_mul_f32_e32 v175, v59, v59
	v_mul_f32_e32 v176, v60, v60
	v_mul_f32_e32 v177, v61, v61
	v_add_u32_e32 v66, v83, v112
	v_lshl_add_u32 v66, v66, 2, v147
	v_mov_b32_dpp v178, v170 quad_perm:[1,0,3,2] row_mask:0xf bank_mask:0xf
	v_mov_b32_dpp v179, v171 quad_perm:[1,0,3,2] row_mask:0xf bank_mask:0xf
	v_mov_b32_dpp v180, v172 quad_perm:[1,0,3,2] row_mask:0xf bank_mask:0xf
	v_mov_b32_dpp v181, v173 quad_perm:[1,0,3,2] row_mask:0xf bank_mask:0xf
	v_mov_b32_dpp v182, v174 quad_perm:[1,0,3,2] row_mask:0xf bank_mask:0xf
	v_mov_b32_dpp v183, v175 quad_perm:[1,0,3,2] row_mask:0xf bank_mask:0xf
	v_mov_b32_dpp v184, v176 quad_perm:[1,0,3,2] row_mask:0xf bank_mask:0xf
	v_mov_b32_dpp v185, v177 quad_perm:[1,0,3,2] row_mask:0xf bank_mask:0xf
	v_fmac_f32_e32 v178, v62, v62
	v_fmac_f32_e32 v179, v63, v63
	v_fmac_f32_e32 v180, v64, v64
	v_fmac_f32_e32 v181, v65, v65
	v_fmac_f32_e32 v182, v58, v58
	v_fmac_f32_e32 v183, v59, v59
	v_fmac_f32_e32 v184, v60, v60
	v_fmac_f32_e32 v185, v61, v61
	v_add_f32_dpp v170, v178, v178 quad_perm:[2,3,0,1] row_mask:0xf bank_mask:0xf bound_ctrl:1
	v_add_f32_dpp v171, v179, v179 quad_perm:[2,3,0,1] row_mask:0xf bank_mask:0xf bound_ctrl:1
	v_add_f32_dpp v172, v180, v180 quad_perm:[2,3,0,1] row_mask:0xf bank_mask:0xf bound_ctrl:1
	v_add_f32_dpp v173, v181, v181 quad_perm:[2,3,0,1] row_mask:0xf bank_mask:0xf bound_ctrl:1
	v_add_f32_dpp v174, v182, v182 quad_perm:[2,3,0,1] row_mask:0xf bank_mask:0xf bound_ctrl:1
	v_add_f32_dpp v175, v183, v183 quad_perm:[2,3,0,1] row_mask:0xf bank_mask:0xf bound_ctrl:1
	v_add_f32_dpp v176, v184, v184 quad_perm:[2,3,0,1] row_mask:0xf bank_mask:0xf bound_ctrl:1
	v_add_f32_dpp v177, v185, v185 quad_perm:[2,3,0,1] row_mask:0xf bank_mask:0xf bound_ctrl:1
	v_add_f32_dpp v170, v170, v170 row_half_mirror row_mask:0xf bank_mask:0xf bound_ctrl:1
	v_add_f32_dpp v171, v171, v171 row_half_mirror row_mask:0xf bank_mask:0xf bound_ctrl:1
	v_add_f32_dpp v172, v172, v172 row_half_mirror row_mask:0xf bank_mask:0xf bound_ctrl:1
	v_add_f32_dpp v173, v173, v173 row_half_mirror row_mask:0xf bank_mask:0xf bound_ctrl:1
	v_add_f32_dpp v174, v174, v174 row_half_mirror row_mask:0xf bank_mask:0xf bound_ctrl:1
	v_add_f32_dpp v175, v175, v175 row_half_mirror row_mask:0xf bank_mask:0xf bound_ctrl:1
	v_add_f32_dpp v176, v176, v176 row_half_mirror row_mask:0xf bank_mask:0xf bound_ctrl:1
	v_add_f32_dpp v177, v177, v177 row_half_mirror row_mask:0xf bank_mask:0xf bound_ctrl:1
	v_mov_b32_dpp v178, v170 row_mirror row_mask:0xf bank_mask:0xf
	v_mov_b32_dpp v179, v171 row_mirror row_mask:0xf bank_mask:0xf
	v_mov_b32_dpp v180, v172 row_mirror row_mask:0xf bank_mask:0xf
	v_mov_b32_dpp v181, v173 row_mirror row_mask:0xf bank_mask:0xf
	v_mov_b32_dpp v182, v174 row_mirror row_mask:0xf bank_mask:0xf
	v_mov_b32_dpp v183, v175 row_mirror row_mask:0xf bank_mask:0xf
	v_mov_b32_dpp v184, v176 row_mirror row_mask:0xf bank_mask:0xf
	v_mov_b32_dpp v185, v177 row_mirror row_mask:0xf bank_mask:0xf
	s_and_saveexec_b64 s[4:5], vcc
	v_add_f32_e32 v170, v170, v178
	v_add_f32_e32 v171, v171, v179
	v_add_f32_e32 v172, v172, v180
	v_add_f32_e32 v173, v173, v181
	v_add_f32_e32 v174, v174, v182
	v_add_f32_e32 v175, v175, v183
	v_add_f32_e32 v176, v176, v184
	v_add_f32_e32 v177, v177, v185
	ds_write_b32 v66, v170
	ds_write_b32 v66, v171 offset:4
	ds_write_b32 v66, v172 offset:8
	ds_write_b32 v66, v173 offset:12
	ds_write_b32 v66, v174 offset:64
	ds_write_b32 v66, v175 offset:68
	ds_write_b32 v66, v176 offset:72
	ds_write_b32 v66, v177 offset:76
	s_or_b64 exec, exec, s[4:5]
	s_andn2_b64 vcc, exec, s[46:47]
	s_cbranch_vccnz .LBB0_190
	s_add_i32 s4, s22, 3
	s_and_b32 s5, s4, 0xff
	s_mulk_i32 s5, 0xab
	s_bfe_u32 s5, s5, 0x70009
	s_mul_i32 s5, s5, 3
	s_sub_i32 s4, s4, s5
	s_and_b32 s4, s4, 0xff
	s_mul_i32 s4, s4, 0x8c00
	v_add_u32_e32 v66, s4, v76
	v_lshl_add_u32 v67, v106, 1, v66
	v_add3_u32 v66, v66, v77, v119
	s_cmp_eq_u32 s22, 28
	s_cbranch_scc0 .Lrv_b2_n0
	s_waitcnt vmcnt(2)
	s_branch .Lrv_b2_end
